# DSA: 13 of 16 up-projection weight fragment loads issued after the last batch's logits (dest registers dead there), flying under softmax/P.V/normalise
# speedup vs baseline: 1.0024x; 1.0024x over previous
;     ...
;     { const int c16 = lane & 15, quad = lane >> 4, hh = wid >> 1;
;       bf16x8 wf[4][4]; u16 zv[4][4];
; #pragma unroll
;       for (int i = 0; i < 4; ++i) { const int d = ((wid & 1) * 4 + i) * 16 + c16; const u16* wp = p.WuvT + ((size_t)hh * 128 + d) * 128 + quad * 8;
; #pragma unroll
;           for (int ks = 0; ks < 4; ++ks) wf[i][ks] = *(const bf16x8*)(wp + ks * 32);
.LBB0_944:
	s_andn2_saveexec_b64 s[0:1], s[0:1]
	s_or_b64 exec, exec, s[0:1]
	s_add_i32 s24, s24, 1
	s_cmp_ge_i32 s24, s23
	v_mov_b32_e32 v78, v124
	v_mov_b32_e32 v79, 0
	v_mov_b32_e32 v71, s59
	v_lshl_add_u64 v[78:79], s[10:11], 0, v[78:79]
	v_and_or_b32 v80, s59, 64, v127
	v_ashrrev_i32_e32 v71, 7, v71
	v_lshlrev_b32_e32 v80, 8, v80
	v_mov_b32_e32 v81, 0
	v_lshl_add_u32 v80, v71, 15, v80
	s_mov_b64 s[0:1], 0x1000
	v_lshl_add_u64 v[74:75], v[78:79], 0, v[80:81]
	global_load_dwordx4 v[26:29], v[74:75], off
	global_load_dwordx4 v[30:33], v[74:75], off offset:64
	global_load_dwordx4 v[66:69], v[74:75], off offset:128
	v_lshl_add_u64 v[80:81], v[74:75], 0, s[0:1]
	global_load_dwordx4 v[50:53], v[80:81], off
	global_load_dwordx4 v[54:57], v[80:81], off offset:64
	global_load_dwordx4 v[58:61], v[80:81], off offset:128
	global_load_dwordx4 v[62:65], v[80:81], off offset:192
	v_lshl_add_u64 v[74:75], v[80:81], 0, s[0:1]
	global_load_dwordx4 v[34:37], v[74:75], off
	global_load_dwordx4 v[38:41], v[74:75], off offset:64
	global_load_dwordx4 v[42:45], v[74:75], off offset:128
	global_load_dwordx4 v[46:49], v[74:75], off offset:192
	v_lshl_add_u64 v[80:81], v[74:75], 0, s[0:1]
	global_load_dwordx4 v[10:13], v[80:81], off offset:128
	global_load_dwordx4 v[14:17], v[80:81], off offset:192

;     ...
;     { const int c16 = lane & 15, quad = lane >> 4, hh = wid >> 1;
;       bf16x8 wf[4][4]; u16 zv[4][4];
; #pragma unroll
;       for (int i = 0; i < 4; ++i) { const int d = ((wid & 1) * 4 + i) * 16 + c16; const u16* wp = p.WuvT + ((size_t)hh * 128 + d) * 128 + quad * 8;
; #pragma unroll
;           for (int ks = 0; ks < 4; ++ks) wf[i][ks] = *(const bf16x8*)(wp + ks * 32);
.Lb5_stub:
	v_mov_b32_e32 v78, v124
	v_mov_b32_e32 v79, 0
	v_mov_b32_e32 v71, s59
	v_lshl_add_u64 v[78:79], s[10:11], 0, v[78:79]
	v_and_or_b32 v80, s59, 64, v127
	v_ashrrev_i32_e32 v71, 7, v71
	v_lshlrev_b32_e32 v80, 8, v80
	v_mov_b32_e32 v81, 0
	v_lshl_add_u32 v80, v71, 15, v80
	s_mov_b64 s[0:1], 0x1000
	v_lshl_add_u64 v[74:75], v[78:79], 0, v[80:81]
	global_load_dwordx4 v[26:29], v[74:75], off
	global_load_dwordx4 v[30:33], v[74:75], off offset:64
	global_load_dwordx4 v[66:69], v[74:75], off offset:128
	v_lshl_add_u64 v[80:81], v[74:75], 0, s[0:1]
	global_load_dwordx4 v[50:53], v[80:81], off
	global_load_dwordx4 v[54:57], v[80:81], off offset:64
	global_load_dwordx4 v[58:61], v[80:81], off offset:128
	global_load_dwordx4 v[62:65], v[80:81], off offset:192
	v_lshl_add_u64 v[74:75], v[80:81], 0, s[0:1]
	global_load_dwordx4 v[34:37], v[74:75], off
	global_load_dwordx4 v[38:41], v[74:75], off offset:64
	global_load_dwordx4 v[42:45], v[74:75], off offset:128
	global_load_dwordx4 v[46:49], v[74:75], off offset:192
	v_lshl_add_u64 v[80:81], v[74:75], 0, s[0:1]
	global_load_dwordx4 v[10:13], v[80:81], off offset:128
	global_load_dwordx4 v[14:17], v[80:81], off offset:192
	s_branch .LBB0_953

; #define LAS __attribute__((address_space(3)))
; __device__ __forceinline__ float bf2f(u16 b) { return __uint_as_float(((unsigned)b) << 16); }
; __device__ __forceinline__ u16 f2bf(float f) { return (u16)(cvtpk(f, 0.f) & 0xffffu); }
; __device__ __forceinline__ float siluf_(float x) { return x * sigmoidf_(x); }
;     ...
;     { const int c16 = lane & 15, quad = lane >> 4, hh = wid >> 1;
;       bf16x8 wf[4][4]; u16 zv[4][4];
; #pragma unroll
;       for (int i = 0; i < 4; ++i) { const int d = ((wid & 1) * 4 + i) * 16 + c16; const u16* wp = p.WuvT + ((size_t)hh * 128 + d) * 128 + quad * 8;
; #pragma unroll
;           for (int ks = 0; ks < 4; ++ks) wf[i][ks] = *(const bf16x8*)(wp + ks * 32);
; #pragma unroll
;           for (int j = 0; j < 4; ++j) zv[i][j] = p.proj[(size_t)(bl * SEQ + t0 + 4 * (quad & 1) + j) * NP + C_BZ + hh * 128 + d]; }
;       __syncthreads();
;       if (sm & 32) {
;           LAS u16* olat = (LAS u16*)(lds + (c16 & 7) * 16384);
;           bf16x8 af[4];
; #pragma unroll
;           for (int ks = 0; ks < 4; ++ks) af[ks] = *(const LAS bf16x8*)(olat + hh * 128 + ks * 32 + quad * 8);
; #pragma unroll
;           for (int i = 0; i < 4; ++i) {
;               const int d = ((wid & 1) * 4 + i) * 16 + c16;
;               f32x4 a = {0.f, 0.f, 0.f, 0.f};
; #pragma unroll
;               for (int ks = 0; ks < 4; ++ks) a = __builtin_amdgcn_mfma_f32_16x16x32_bf16(af[ks], wf[i][ks], a, 0, 0, 0);
;               if (quad < 2 && sm == 63) {
; #pragma unroll
;                   for (int j = 0; j < 4; ++j) { const size_t grow = (size_t)(bl * SEQ + t0 + 4 * quad + j);
;                       p.ybuf[((size_t)1 * MG + grow) * 512 + hh * 128 + d] = f2bf(a[j] * siluf_(bf2f(zv[i][j]))); }
.LBB0_961:
	s_or_b64 exec, exec, s[0:1]
	s_lshl_b32 s26, s37, 12
	v_lshlrev_b32_e32 v70, 2, v128
	s_add_i32 s0, s30, s26
	v_and_or_b32 v0, v70, 4, s0
	s_and_b32 s0, s59, 0xffffff80
	v_mul_i32_i24_e32 v0, 0x5800, v0
	s_ashr_i32 s20, s59, 7
	s_ashr_i32 s1, s0, 31
	s_waitcnt lgkmcnt(0)
	v_lshl_add_u64 v[4:5], s[14:15], 0, v[0:1]
	v_and_or_b32 v0, s59, 64, v127
	s_ashr_i32 s21, s20, 31
	v_lshlrev_b32_e32 v6, 8, v0
	v_lshlrev_b32_e32 v0, 1, v0
	v_lshl_add_u64 v[4:5], s[0:1], 1, v[4:5]
	s_lshl_b64 s[22:23], s[20:21], 15
	v_lshl_add_u64 v[4:5], v[4:5], 0, v[0:1]
	s_movk_i32 s21, 0x1000
	v_add_co_u32_e32 v20, vcc, s21, v4
	s_movk_i32 s21, 0x6000
	s_nop 0
	v_addc_co_u32_e32 v21, vcc, 0, v5, vcc
	v_add_co_u32_e32 v24, vcc, s21, v4
	s_mov_b64 s[24:25], 0x1400
	s_nop 0
	v_addc_co_u32_e32 v25, vcc, 0, v5, vcc
	s_mov_b32 s21, 0xc000
	v_lshl_add_u64 v[18:19], v[4:5], 0, s[24:25]
	s_mov_b64 s[24:25], 0x6c00
	v_add_co_u32_e32 v72, vcc, s21, v4
	v_lshl_add_u64 v[22:23], v[4:5], 0, s[24:25]
	s_mov_b64 s[24:25], 0xc400
	v_addc_co_u32_e32 v73, vcc, 0, v5, vcc
	s_mov_b32 s21, 0x11000
	v_mov_b32_e32 v125, v1
	v_lshl_add_u64 v[92:93], v[4:5], 0, s[24:25]
	s_mov_b64 s[24:25], 0x11c00
	v_add_co_u32_e32 v76, vcc, s21, v4
	v_lshl_add_u64 v[2:3], s[10:11], 0, v[124:125]
	v_mov_b32_e32 v7, v1
	v_lshl_add_u64 v[94:95], v[4:5], 0, s[24:25]
	v_addc_co_u32_e32 v77, vcc, 0, v5, vcc
	v_or_b32_e32 v4, 0x1000, v6
	v_mov_b32_e32 v5, v1
	v_lshl_add_u64 v[8:9], v[2:3], 0, v[6:7]
	v_lshl_add_u64 v[4:5], v[2:3], 0, v[4:5]
	v_lshl_add_u64 v[8:9], v[8:9], 0, s[22:23]
	v_lshl_add_u64 v[4:5], v[4:5], 0, s[22:23]
	global_load_dwordx4 v[88:91], v[8:9], off offset:192
	v_or_b32_e32 v4, 0x2000, v6
	v_mov_b32_e32 v5, v1
	v_lshl_add_u64 v[4:5], v[2:3], 0, v[4:5]
	v_lshl_add_u64 v[4:5], v[4:5], 0, s[22:23]
	v_or_b32_e32 v4, 0x3000, v6
	v_mov_b32_e32 v5, v1
	v_lshl_add_u64 v[2:3], v[2:3], 0, v[4:5]
	v_lshl_add_u64 v[74:75], v[2:3], 0, s[22:23]
	global_load_dwordx4 v[2:5], v[74:75], off
	global_load_dwordx4 v[6:9], v[74:75], off offset:64
	s_nop 0
	s_nop 0
	global_load_ushort v71, v[20:21], off offset:1024
	global_load_ushort v86, v[24:25], off offset:3072
	global_load_ushort v83, v[18:19], off offset:32
	global_load_ushort v82, v[22:23], off offset:32
	global_load_ushort v79, v[18:19], off offset:64
	global_load_ushort v78, v[22:23], off offset:64
	global_load_ushort v74, v[22:23], off offset:96
	global_load_ushort v75, v[18:19], off offset:96
	global_load_ushort v85, v[72:73], off offset:1024
	global_load_ushort v84, v[76:77], off offset:3072
	global_load_ushort v81, v[92:93], off offset:32
	global_load_ushort v80, v[94:95], off offset:32
	s_nop 0
	global_load_ushort v77, v[92:93], off offset:64
	global_load_ushort v76, v[94:95], off offset:64
	global_load_ushort v72, v[94:95], off offset:96
	global_load_ushort v73, v[92:93], off offset:96
	v_lshlrev_b32_e32 v18, 14, v163
	s_lshl_b32 s20, s20, 8
	v_and_b32_e32 v18, 0x1c000, v18
	s_add_i32 s20, s20, 0
	v_add3_u32 v87, s20, v18, v126
	s_barrier
	ds_read_b128 v[18:21], v87
	ds_read_b128 v[22:25], v87 offset:64
	v_or_b32_e32 v70, s26, v70
	v_add_u32_e32 v70, s30, v70
	v_cmp_gt_u32_e64 s[38:39], 32, v163
	v_lshlrev_b32_e32 v70, 10, v70
	s_waitcnt vmcnt(19) lgkmcnt(1)
	v_mfma_f32_16x16x32_bf16 v[92:95], v[18:21], v[26:29], 0
	ds_read_b128 v[26:29], v87 offset:128
	s_waitcnt vmcnt(19) lgkmcnt(1)
	v_mfma_f32_16x16x32_bf16 v[92:95], v[22:25], v[30:33], v[92:95]
	ds_read_b128 v[30:33], v87 offset:192
	s_waitcnt vmcnt(19) lgkmcnt(1)
	v_mfma_f32_16x16x32_bf16 v[66:69], v[26:29], v[66:69], v[92:95]
	s_waitcnt vmcnt(18) lgkmcnt(0)
	v_mfma_f32_16x16x32_bf16 v[66:69], v[30:33], v[88:91], v[66:69]
	s_and_saveexec_b64 s[20:21], s[38:39]
	s_cbranch_execz .LBB0_963
	s_waitcnt vmcnt(15)
	v_lshlrev_b32_e32 v71, 16, v71
	v_mul_f32_e32 v87, 0xbfb8aa3b, v71
	v_exp_f32_e32 v87, v87
	s_mov_b32 s22, 0x1000000
	v_add_f32_e32 v87, 1.0, v87
	v_rcp_f32_e32 v87, v87
	s_nop 0
	v_mul_f32_e32 v71, v87, v71
	v_mul_f32_e32 v66, v71, v66
	v_mov_b32_e32 v71, v1
	v_lshl_add_u64 v[88:89], s[16:17], 0, v[70:71]
	v_lshl_add_u64 v[88:89], s[0:1], 1, v[88:89]
	v_lshl_add_u64 v[88:89], v[88:89], 0, v[0:1]
	v_add_co_u32_e32 v88, vcc, s22, v88
	v_cvt_pk_bf16_f32 v66, v66, v1
	s_nop 1
	v_addc_co_u32_e32 v89, vcc, 0, v89, vcc
	global_store_short v[88:89], v66, off
	s_waitcnt vmcnt(15)
	v_lshlrev_b32_e32 v66, 16, v86
	v_mul_f32_e32 v71, 0xbfb8aa3b, v66
	v_exp_f32_e32 v71, v71
	s_nop 0
	v_add_f32_e32 v71, 1.0, v71
	v_rcp_f32_e32 v71, v71
	s_nop 0
	v_mul_f32_e32 v66, v71, v66
	v_mul_f32_e32 v66, v66, v67
	v_cvt_pk_bf16_f32 v66, v66, v1
	global_store_short v[88:89], v66, off offset:1024
	s_waitcnt vmcnt(9)
	v_lshlrev_b32_e32 v66, 16, v85
	v_mul_f32_e32 v67, 0xbfb8aa3b, v66
	v_exp_f32_e32 v67, v67
	s_nop 0
	v_add_f32_e32 v67, 1.0, v67
	v_rcp_f32_e32 v67, v67
	s_nop 0
	v_mul_f32_e32 v66, v67, v66
	v_mul_f32_e32 v66, v66, v68
	v_cvt_pk_bf16_f32 v66, v66, v1
	global_store_short v[88:89], v66, off offset:2048
	s_waitcnt vmcnt(9)
	v_lshlrev_b32_e32 v66, 16, v84
	v_mul_f32_e32 v67, 0xbfb8aa3b, v66
	v_exp_f32_e32 v67, v67
	s_nop 0
	v_add_f32_e32 v67, 1.0, v67
	v_rcp_f32_e32 v67, v67
	s_nop 0
	v_mul_f32_e32 v66, v67, v66
	v_mul_f32_e32 v66, v66, v69
	v_cvt_pk_bf16_f32 v66, v66, v1
	global_store_short v[88:89], v66, off offset:3072
; __device__ __forceinline__ float bf2f(u16 b) { return __uint_as_float(((unsigned)b) << 16); }
; __device__ __forceinline__ u16 f2bf(float f) { return (u16)(cvtpk(f, 0.f) & 0xffffu); }
; __device__ __forceinline__ float siluf_(float x) { return x * sigmoidf_(x); }
;     ...
;           for (int i = 0; i < 4; ++i) {
;               const int d = ((wid & 1) * 4 + i) * 16 + c16;
;               f32x4 a = {0.f, 0.f, 0.f, 0.f};
; #pragma unroll
;               for (int ks = 0; ks < 4; ++ks) a = __builtin_amdgcn_mfma_f32_16x16x32_bf16(af[ks], wf[i][ks], a, 0, 0, 0);
;               if (quad < 2 && sm == 63) {
; #pragma unroll
;                   for (int j = 0; j < 4; ++j) { const size_t grow = (size_t)(bl * SEQ + t0 + 4 * quad + j);
;                       p.ybuf[((size_t)1 * MG + grow) * 512 + hh * 128 + d] = f2bf(a[j] * siluf_(bf2f(zv[i][j]))); }
.LBB0_963:
	s_or_b64 exec, exec, s[20:21]
	s_waitcnt vmcnt(19)
	v_mfma_f32_16x16x32_bf16 v[50:53], v[18:21], v[50:53], 0
	s_waitcnt vmcnt(19)
	v_mfma_f32_16x16x32_bf16 v[50:53], v[22:25], v[54:57], v[50:53]
	s_waitcnt vmcnt(19)
	v_mfma_f32_16x16x32_bf16 v[50:53], v[26:29], v[58:61], v[50:53]
	s_waitcnt vmcnt(19)
	v_mfma_f32_16x16x32_bf16 v[50:53], v[30:33], v[62:65], v[50:53]
	s_and_saveexec_b64 s[20:21], s[38:39]
	s_cbranch_execz .LBB0_965
	s_waitcnt vmcnt(13)
	v_lshlrev_b32_e32 v54, 16, v83
	v_mul_f32_e32 v55, 0xbfb8aa3b, v54
	v_exp_f32_e32 v55, v55
	v_mov_b32_e32 v71, v1
	s_mov_b32 s22, 0x1000000
	v_add_f32_e32 v55, 1.0, v55
	v_rcp_f32_e32 v55, v55
	s_nop 0
	v_mul_f32_e32 v54, v55, v54
	v_mul_f32_e32 v50, v54, v50
	v_lshl_add_u64 v[54:55], s[16:17], 0, v[70:71]
	v_lshl_add_u64 v[54:55], s[0:1], 1, v[54:55]
	v_lshl_add_u64 v[54:55], v[54:55], 0, v[0:1]
	v_add_co_u32_e32 v54, vcc, s22, v54
	v_cvt_pk_bf16_f32 v50, v50, v1
	s_nop 1
	v_addc_co_u32_e32 v55, vcc, 0, v55, vcc
	global_store_short v[54:55], v50, off offset:32
	s_waitcnt vmcnt(13)
	v_lshlrev_b32_e32 v50, 16, v82
	v_mul_f32_e32 v56, 0xbfb8aa3b, v50
	v_exp_f32_e32 v56, v56
	s_nop 0
	v_add_f32_e32 v56, 1.0, v56
	v_rcp_f32_e32 v56, v56
	s_nop 0
	v_mul_f32_e32 v50, v56, v50
	v_mul_f32_e32 v50, v50, v51
	v_cvt_pk_bf16_f32 v50, v50, v1
	global_store_short v[54:55], v50, off offset:1056
	s_waitcnt vmcnt(7)
	v_lshlrev_b32_e32 v50, 16, v81
	v_mul_f32_e32 v51, 0xbfb8aa3b, v50
	v_exp_f32_e32 v51, v51
	s_nop 0
	v_add_f32_e32 v51, 1.0, v51
	v_rcp_f32_e32 v51, v51
	s_nop 0
	v_mul_f32_e32 v50, v51, v50
	v_mul_f32_e32 v50, v50, v52
	v_cvt_pk_bf16_f32 v50, v50, v1
	global_store_short v[54:55], v50, off offset:2080
	s_waitcnt vmcnt(7)
	v_lshlrev_b32_e32 v50, 16, v80
	v_mul_f32_e32 v51, 0xbfb8aa3b, v50
	v_exp_f32_e32 v51, v51
	s_nop 0
	v_add_f32_e32 v51, 1.0, v51
	v_rcp_f32_e32 v51, v51
	s_nop 0
	v_mul_f32_e32 v50, v51, v50
	v_mul_f32_e32 v50, v50, v53
	v_cvt_pk_bf16_f32 v50, v50, v1
	global_store_short v[54:55], v50, off offset:3104
.LBB0_965:
	s_or_b64 exec, exec, s[20:21]
	s_waitcnt vmcnt(19)
	v_mfma_f32_16x16x32_bf16 v[34:37], v[18:21], v[34:37], 0
	s_waitcnt vmcnt(19)
	v_mfma_f32_16x16x32_bf16 v[34:37], v[22:25], v[38:41], v[34:37]
	s_waitcnt vmcnt(19)
	v_mfma_f32_16x16x32_bf16 v[34:37], v[26:29], v[42:45], v[34:37]
	s_waitcnt vmcnt(19)
	v_mfma_f32_16x16x32_bf16 v[34:37], v[30:33], v[46:49], v[34:37]
	s_and_saveexec_b64 s[20:21], s[38:39]
	s_cbranch_execz .LBB0_967
	s_waitcnt vmcnt(11)
	v_lshlrev_b32_e32 v38, 16, v79
	v_mul_f32_e32 v39, 0xbfb8aa3b, v38
	v_exp_f32_e32 v39, v39
	v_mov_b32_e32 v71, v1
	s_mov_b32 s22, 0x1000000
	v_add_f32_e32 v39, 1.0, v39
	v_rcp_f32_e32 v39, v39
	s_nop 0
	v_mul_f32_e32 v38, v39, v38
	v_mul_f32_e32 v34, v38, v34
	v_lshl_add_u64 v[38:39], s[16:17], 0, v[70:71]
	v_lshl_add_u64 v[38:39], s[0:1], 1, v[38:39]
	v_lshl_add_u64 v[38:39], v[38:39], 0, v[0:1]
	v_add_co_u32_e32 v38, vcc, s22, v38
	v_cvt_pk_bf16_f32 v34, v34, v1
	s_nop 1
	v_addc_co_u32_e32 v39, vcc, 0, v39, vcc
	global_store_short v[38:39], v34, off offset:64
	s_waitcnt vmcnt(11)
	v_lshlrev_b32_e32 v34, 16, v78
	v_mul_f32_e32 v40, 0xbfb8aa3b, v34
	v_exp_f32_e32 v40, v40
	s_nop 0
	v_add_f32_e32 v40, 1.0, v40
	v_rcp_f32_e32 v40, v40
	s_nop 0
	v_mul_f32_e32 v34, v40, v34
	v_mul_f32_e32 v34, v34, v35
	v_cvt_pk_bf16_f32 v34, v34, v1
	global_store_short v[38:39], v34, off offset:1088
	s_waitcnt vmcnt(5)
	v_lshlrev_b32_e32 v34, 16, v77
	v_mul_f32_e32 v35, 0xbfb8aa3b, v34
	v_exp_f32_e32 v35, v35
	s_nop 0
	v_add_f32_e32 v35, 1.0, v35
	v_rcp_f32_e32 v35, v35
	s_nop 0
	v_mul_f32_e32 v34, v35, v34
	v_mul_f32_e32 v34, v34, v36
	v_cvt_pk_bf16_f32 v34, v34, v1
	global_store_short v[38:39], v34, off offset:2112
	s_waitcnt vmcnt(5)
	v_lshlrev_b32_e32 v34, 16, v76
	v_mul_f32_e32 v35, 0xbfb8aa3b, v34
	v_exp_f32_e32 v35, v35
	s_nop 0
	v_add_f32_e32 v35, 1.0, v35
	v_rcp_f32_e32 v35, v35
	s_nop 0
	v_mul_f32_e32 v34, v35, v34
	v_mul_f32_e32 v34, v34, v37
	v_cvt_pk_bf16_f32 v34, v34, v1
	global_store_short v[38:39], v34, off offset:3136
.LBB0_967:
	s_or_b64 exec, exec, s[20:21]
	s_waitcnt vmcnt(17)
	v_mfma_f32_16x16x32_bf16 v[2:5], v[18:21], v[2:5], 0
	s_waitcnt vmcnt(16)
	v_mfma_f32_16x16x32_bf16 v[2:5], v[22:25], v[6:9], v[2:5]
	s_waitcnt vmcnt(16)
	v_mfma_f32_16x16x32_bf16 v[2:5], v[26:29], v[10:13], v[2:5]
	s_waitcnt vmcnt(16)
	v_mfma_f32_16x16x32_bf16 v[2:5], v[30:33], v[14:17], v[2:5]
	s_and_saveexec_b64 s[20:21], s[38:39]
	s_cbranch_execz .LBB0_969
	s_waitcnt vmcnt(8)
	v_lshlrev_b32_e32 v6, 16, v75
	v_mul_f32_e32 v7, 0xbfb8aa3b, v6
	v_exp_f32_e32 v7, v7
	v_mov_b32_e32 v71, v1
	v_add_f32_e32 v7, 1.0, v7
	v_rcp_f32_e32 v7, v7
	s_nop 0
	v_mul_f32_e32 v6, v7, v6
	v_mul_f32_e32 v2, v6, v2
	v_lshl_add_u64 v[6:7], s[16:17], 0, v[70:71]
	v_lshl_add_u64 v[6:7], s[0:1], 1, v[6:7]
	v_lshl_add_u64 v[6:7], v[6:7], 0, v[0:1]
	s_mov_b32 s0, 0x1000000
	v_add_co_u32_e32 v6, vcc, s0, v6
	v_cvt_pk_bf16_f32 v2, v2, v1
	v_lshlrev_b32_e32 v0, 16, v74
	s_nop 0
	v_addc_co_u32_e32 v7, vcc, 0, v7, vcc
	global_store_short v[6:7], v2, off offset:96
	v_mul_f32_e32 v2, 0xbfb8aa3b, v0
	v_exp_f32_e32 v2, v2
	s_nop 0
	v_add_f32_e32 v2, 1.0, v2
	v_rcp_f32_e32 v2, v2
	s_nop 0
	v_mul_f32_e32 v0, v2, v0
	v_mul_f32_e32 v0, v0, v3
	v_cvt_pk_bf16_f32 v0, v0, v1
	global_store_short v[6:7], v0, off offset:1120
	s_waitcnt vmcnt(2)
	v_lshlrev_b32_e32 v0, 16, v73
	v_mul_f32_e32 v2, 0xbfb8aa3b, v0
	v_exp_f32_e32 v2, v2
	s_nop 0
	v_add_f32_e32 v2, 1.0, v2
	v_rcp_f32_e32 v2, v2
	s_nop 0
	v_mul_f32_e32 v0, v2, v0
	v_mul_f32_e32 v0, v0, v4
	v_cvt_pk_bf16_f32 v0, v0, v1
	global_store_short v[6:7], v0, off offset:2144
	v_lshlrev_b32_e32 v0, 16, v72
	v_mul_f32_e32 v2, 0xbfb8aa3b, v0
	v_exp_f32_e32 v2, v2
	s_nop 0
	v_add_f32_e32 v2, 1.0, v2
	v_rcp_f32_e32 v2, v2
	s_nop 0
	v_mul_f32_e32 v0, v2, v0
	v_mul_f32_e32 v0, v0, v5
	v_cvt_pk_bf16_f32 v0, v0, v1
	global_store_short v[6:7], v0, off offset:3168
